# PRE phase: each workgroup walks its 16 task pairs starting at a round rotated by its index, mixing weight transposes and cache conversions in time
# speedup vs baseline: 1.0129x; 1.0003x over previous
.Lpre_skip:
	s_add_i32 s8, s8, s64
	s_movk_i32 s38, 0xfcf
	s_cmp_eq_u32 s64, 0x100
	s_cselect_b32 s38, 0xfff, s38
	s_cmp_gt_i32 s8, s38
	s_cbranch_scc1 .LBB0_7
.LBB0_787:
	s_mov_b32 s36, s8
	s_cmp_lg_u32 s64, 0x100
	s_cbranch_scc1 .Lpre_norot
	s_lshr_b32 s36, s8, 8
	s_add_i32 s36, s36, s8
	s_and_b32 s36, s36, 15
	s_lshl_b32 s36, s36, 8
	s_and_b32 s37, s8, 0xff
	s_or_b32 s36, s36, s37
	s_cmpk_gt_i32 s36, 0xfcf
	s_cbranch_scc1 .Lpre_skip
.Lpre_norot:
	v_lshl_add_u32 v6, s36, 1, v33
	v_cmp_lt_i32_e32 vcc, s4, v6
	s_and_saveexec_b64 s[18:19], vcc
	s_xor_b64 s[18:19], exec, s[18:19]
	s_cbranch_execz .LBB0_825
	s_movk_i32 s17, 0xdf
	v_cmp_lt_u32_e32 vcc, s17, v6
	s_and_saveexec_b64 s[20:21], vcc
	s_xor_b64 s[42:43], exec, s[20:21]
	s_cbranch_execz .LBB0_822
	s_movk_i32 s17, 0x119f
	v_cmp_lt_u32_e32 vcc, s17, v6
	s_and_saveexec_b64 s[20:21], vcc
	s_xor_b64 s[20:21], exec, s[20:21]
	s_cbranch_execz .LBB0_803
	s_movk_i32 s17, 0x129f
	v_cmp_lt_u32_e32 vcc, s17, v6
	s_and_saveexec_b64 s[22:23], vcc
	s_xor_b64 s[22:23], exec, s[22:23]
	s_cbranch_execz .LBB0_800
	s_movk_i32 s17, 0x139f
	v_cmp_lt_u32_e32 vcc, s17, v6
	s_and_saveexec_b64 s[24:25], vcc
	s_xor_b64 s[24:25], exec, s[24:25]
	s_cbranch_execz .LBB0_797
	s_movk_i32 s17, 0x1b9f
	v_cmp_lt_u32_e32 vcc, s17, v6
	s_and_saveexec_b64 s[26:27], vcc
	s_xor_b64 s[26:27], exec, s[26:27]
	s_cbranch_execz .LBB0_794
	v_add_u32_e32 v10, 0xffffe460, v6
	s_movk_i32 s17, 0x200
	v_cmp_gt_u32_e32 vcc, s17, v10
	v_readlane_b32 s28, v253, 1
	v_readlane_b32 s29, v253, 2
	v_cndmask_b32_e64 v0, 48, 32, vcc
	s_mov_b32 s17, 0x1ff00
	v_lshl_add_u64 v[2:3], s[28:29], 0, v[0:1]
	global_load_dwordx2 v[2:3], v[2:3], off
	v_lshlrev_b32_e32 v0, 8, v10
	v_and_or_b32 v12, v0, s17, v27
	v_lshlrev_b32_e32 v0, 5, v12
	v_lshrrev_b32_e32 v14, 6, v10
	v_bfe_u32 v13, v10, 5, 2
	s_mov_b32 s17, 0x1200000
	v_mul_lo_u32 v10, v13, s17
	v_lshrrev_b32_e32 v12, 4, v12
	v_readlane_b32 s28, v254, 30
	s_movk_i32 s17, 0x1ff
	v_mov_b32_e32 v11, v1
	v_readlane_b32 s29, v254, 31
	v_mov_b32_e32 v13, 0x600000
	s_waitcnt vmcnt(0)
	v_lshl_add_u64 v[6:7], v[2:3], 0, v[0:1]
	global_load_dwordx4 v[2:5], v[6:7], off nt
	s_nop 0
	global_load_dwordx4 v[6:9], v[6:7], off offset:16 nt
	v_lshlrev_b32_e32 v0, 4, v27
	v_and_b32_e32 v15, 0x70, v0
	v_and_or_b32 v0, v14, 6, v39
	v_mul_u32_u24_e32 v0, 0x600, v0
	v_and_or_b32 v12, v12, s17, v0
	v_mov_b32_e32 v0, 0x780000
	v_lshl_add_u64 v[10:11], s[28:29], 0, v[10:11]
	v_cndmask_b32_e32 v0, v0, v13, vcc
	v_lshl_add_u64 v[10:11], v[10:11], 0, v[0:1]
	v_lshl_or_b32 v0, v12, 7, v15
	v_lshl_add_u64 v[10:11], v[10:11], 0, v[0:1]
	s_waitcnt vmcnt(1)
	v_cvt_pk_bf16_f32 v2, v2, v3
	v_cvt_pk_bf16_f32 v3, v4, v5
	s_waitcnt vmcnt(0)
	v_cvt_pk_bf16_f32 v4, v6, v7
	v_cvt_pk_bf16_f32 v5, v8, v9
	global_store_dwordx4 v[10:11], v[2:5], off
